# mixer-phase roles handed out by the logical id with its two low 3-bit fields swapped: Fourier workgroups spread over all XCDs, each gMLP workgroup reads the h block of its own XCD
# baseline (speedup 1.0000x reference)
.LBB0_939:
	s_or_b64 exec, exec, s[12:13]
	v_cvt_f32_u32_e32 v4, v2
	s_waitcnt vmcnt(0)
	v_readfirstlane_b32 s2, v3
	v_sub_u32_e32 v3, 0, v2
	v_rcp_iflag_f32_e32 v4, v4
	v_add_u32_e32 v5, s2, v1
	v_mul_f32_e32 v4, 0x4f7ffffe, v4
	v_cvt_u32_f32_e32 v4, v4
	v_mul_lo_u32 v1, v3, v4
	v_mul_hi_u32 v1, v4, v1
	v_add_u32_e32 v1, v4, v1
	v_mul_hi_u32 v1, v5, v1
	v_mul_lo_u32 v3, v1, v2
	v_sub_u32_e32 v3, v5, v3
	v_add_u32_e32 v4, 1, v1
	v_cmp_ge_u32_e32 vcc, v3, v2
	s_nop 1
	v_cndmask_b32_e32 v1, v1, v4, vcc
	v_sub_u32_e32 v4, v3, v2
	v_cndmask_b32_e32 v3, v3, v4, vcc
	v_add_u32_e32 v4, 1, v1
	v_cmp_ge_u32_e32 vcc, v3, v2
	v_add_u32_e32 v3, 1, v5
	s_nop 0
	v_cndmask_b32_e32 v1, v1, v4, vcc
	v_mul_lo_u32 v4, v2, v1
	v_add_u32_e32 v2, v4, v2
	v_cmp_ne_u32_e32 vcc, v3, v2
	s_and_saveexec_b64 s[10:11], vcc
	s_xor_b64 s[10:11], exec, s[10:11]
	s_cbranch_execz .LBB0_953
	v_readlane_b32 s18, v255, 0
	s_nop 0
	s_cmp_lt_u32 s18, 64
	s_cbranch_scc0 .Lb5_std
	s_bfe_u32 s19, s18, 0x30003
	s_and_b32 s18, s18, 3
	s_lshl_b32 s18, s18, 3
	s_or_b32 s18, s18, s19
	s_lshl_b32 s18, s18, 7
	s_add_u32 s18, s18, 0xb000
	v_readlane_b32 s19, v255, 47
	v_mov_b32_e32 v0, s18
	s_mov_b32 s2, 0
	s_waitcnt lgkmcnt(0)

.LBB0_973:
	s_or_b64 exec, exec, s[4:5]
	s_waitcnt lgkmcnt(0)
	s_barrier
	s_load_dwordx2 s[4:5], s[16:17], 0x98
	v_readlane_b32 s2, v255, 0
	s_nop 0
	s_and_b32 s6, s2, 7
	s_lshl_b32 s6, s6, 3
	s_bfe_u32 s7, s2, 0x30003
	s_or_b32 s6, s6, s7
	s_and_b32 s2, s2, 0xc0
	s_or_b32 s2, s2, s6
	v_mov_b32_e32 v166, v147
	s_cmp_gt_i32 s2, 63
	v_readfirstlane_b32 s20, v166
	s_mov_b64 s[6:7], -1
	s_cbranch_scc0 .LBB0_992
	s_cmpk_gt_u32 s2, 0x5f
	s_mov_b64 s[56:57], s[16:17]
	s_cbranch_scc1 .LBB0_991
	v_mov_b32_e32 v11, v147
	s_sub_i32 s6, s2, 64
	s_cmp_gt_u32 s6, 15
	v_readfirstlane_b32 s18, v11
	s_cbranch_scc1 .LBB0_983
	v_lshlrev_b32_e32 v0, 4, v11
	v_add_u32_e32 v1, 0x2000, v0
	v_ashrrev_i32_e32 v2, 31, v1
	v_lshrrev_b32_e32 v2, 22, v2
	v_add_u32_e32 v2, v1, v2
	v_ashrrev_i32_e32 v8, 10, v2
	v_mul_i32_i24_e32 v2, 0x400, v8
	v_sub_u32_e32 v1, v1, v2
	v_lshrrev_b32_e32 v2, 4, v1
	v_bitop3_b32 v1, v2, v1, 32 bitop3:0x6c
	v_ashrrev_i32_e32 v2, 31, v1
	v_lshrrev_b32_e32 v2, 26, v2
	v_add_u32_e32 v2, v1, v2
	v_lshlrev_b32_e32 v3, 3, v8
	v_ashrrev_i32_e32 v9, 6, v2
	v_and_b32_e32 v3, -16, v3
	v_add_u32_e32 v3, v9, v3
	v_and_b32_e32 v4, 3, v9
	s_mov_b32 s7, 0xfffe0
	v_lshrrev_b32_e32 v5, 2, v3
	v_lshlrev_b32_e32 v6, 1, v3
	v_and_b32_e32 v2, 0xc0, v2
	v_and_or_b32 v4, v3, s7, v4
	v_and_b32_e32 v5, 4, v5
	v_and_b32_e32 v6, 24, v6
	v_sub_u32_e32 v1, v1, v2
	v_or3_b32 v4, v4, v5, v6
	v_lshlrev_b32_e32 v5, 5, v8
	v_ashrrev_i16_sdwa v1, v189, sext(v1) dst_sel:DWORD dst_unused:UNUSED_PAD src0_sel:DWORD src1_sel:BYTE_0
	v_and_b32_e32 v5, 32, v5
	v_bfe_i32 v10, v1, 0, 16
	v_add_lshl_u32 v1, v5, v10, 1
	v_lshl_add_u32 v130, v4, 12, v1
	v_lshl_add_u32 v132, v3, 12, v1
	v_bfe_i32 v1, v11, 27, 1
	v_lshrrev_b32_e32 v1, 22, v1
	v_add_u32_e32 v1, v0, v1
	v_and_b32_e32 v1, 0xfffffc00, v1
	v_sub_u32_e32 v0, v0, v1
	v_lshrrev_b32_e32 v1, 4, v0
	v_bitop3_b32 v1, v1, v0, 32 bitop3:0x6c
	v_ashrrev_i32_e32 v0, 31, v0
	v_lshrrev_b32_e32 v0, 26, v0
	v_add_u32_e32 v0, v1, v0
	v_ashrrev_i32_e32 v12, 6, v0
	v_ashrrev_i32_e32 v0, 31, v11
	v_lshrrev_b32_e32 v0, 26, v0
	v_add_u32_e32 v0, v11, v0
	v_ashrrev_i32_e32 v13, 6, v0
	v_lshlrev_b32_e32 v0, 3, v13
	v_and_b32_e32 v0, -16, v0
	v_add_u32_e32 v0, v12, v0
	v_and_b32_e32 v2, 3, v12
	v_lshrrev_b32_e32 v3, 2, v0
	v_lshlrev_b32_e32 v4, 1, v0
	s_ashr_i32 s10, s18, 6
	v_and_or_b32 v2, v0, s7, v2
	v_and_b32_e32 v3, 4, v3
	v_and_b32_e32 v4, 24, v4
	s_and_b32 s21, s2, 3
	s_lshr_b32 s22, s6, 2
	s_ashr_i32 s11, s18, 8
	s_lshl_b32 s19, s10, 10
	v_or3_b32 v2, v2, v3, v4
	v_mul_i32_i24_e32 v4, 64, v12
	s_lshl_b32 s13, s21, 20
	s_lshl_b32 s12, s22, 20
	v_sub_u32_e32 v1, v1, v4
	s_waitcnt lgkmcnt(0)
	s_add_u32 s8, s4, s12
	v_lshlrev_b32_e32 v3, 5, v13
	v_ashrrev_i16_sdwa v1, v189, sext(v1) dst_sel:DWORD dst_unused:UNUSED_PAD src0_sel:DWORD src1_sel:BYTE_0
	s_addc_u32 s9, s5, 0
	v_and_b32_e32 v3, 32, v3
	v_bfe_i32 v14, v1, 0, 16
	s_add_u32 s6, s8, 0x3c00000
	v_add_lshl_u32 v1, v3, v14, 1
	s_addc_u32 s7, s9, 0
	s_add_i32 s23, s19, 0
	v_lshl_add_u32 v144, v2, 12, v1
	s_add_i32 m0, s23, 0x10000
	v_lshl_add_u32 v134, v0, 12, v1
	global_load_lds_dwordx4 v144, s[6:7]
	s_add_i32 m0, s23, 0x12000
	s_add_u32 s8, s8, 0x3c80000
	global_load_lds_dwordx4 v130, s[6:7]
	s_addc_u32 s9, s9, 0
	s_add_i32 m0, s23, 0x14000
	v_mov_b32_e32 v131, v145
	global_load_lds_dwordx4 v144, s[8:9]
	s_add_i32 m0, s23, 0x16000
	s_add_u32 s14, s4, s13
	s_addc_u32 s15, s5, 0
	global_load_lds_dwordx4 v130, s[8:9]
	s_add_u32 s8, s14, 0x200000
	s_addc_u32 s9, s15, 0
	s_add_i32 s24, s23, 0x2000
	s_mov_b32 m0, s23
	s_add_u32 s14, s14, 0x280000
	global_load_lds_dwordx4 v134, s[8:9]
	s_mov_b32 m0, s24
	s_addc_u32 s15, s15, 0
	s_add_i32 s25, s23, 0x4000
	global_load_lds_dwordx4 v132, s[8:9]
	s_mov_b32 m0, s25
	s_add_i32 s26, s23, 0x6000
	global_load_lds_dwordx4 v134, s[14:15]
	s_mov_b32 m0, s26
	v_mov_b32_e32 v135, v145
	global_load_lds_dwordx4 v132, s[14:15]
	v_mov_b32_e32 v133, v145
	v_lshl_add_u64 v[6:7], s[6:7], 0, v[144:145]
	v_lshl_add_u64 v[4:5], s[6:7], 0, v[130:131]
	v_lshl_add_u64 v[2:3], s[8:9], 0, v[134:135]
	s_cmp_lg_u32 s11, 1
	v_lshl_add_u64 v[0:1], s[8:9], 0, v[132:133]
	s_cbranch_scc1 .LBB0_978
	s_barrier
